# residual+norm epilogues: xin loads of row groups 1..7 prefetched 3 pairs ahead into free registers (was 2 loads per serialized round trip)
# speedup vs baseline: 1.0436x; 1.0091x over previous
.LBB0_36:
	s_ashr_i32 s2, s88, 4
	v_and_b32_e32 v76, 64, v203
	s_lshl_b32 s17, s10, 5
	s_lshl_b32 s11, s88, 8
	s_lshl_b32 s22, s90, 8
	s_mul_hi_i32 s3, s2, 0x6000
	s_mulk_i32 s2, 0x6000
	v_readlane_b32 s40, v254, 41
	v_xor_b32_e32 v75, 16, v203
	v_add_u32_e32 v76, 64, v76
	v_mov_b32_e32 v164, v203
	v_readlane_b32 s41, v254, 42
	s_add_u32 s2, s40, s2
	v_cmp_lt_i32_e32 vcc, v75, v76
	s_waitcnt vmcnt(0)
	s_barrier
	s_waitcnt vmcnt(0)
	s_barrier
	s_addc_u32 s3, s41, s3
	v_bfe_u32 v74, v164, 4, 2
	s_or_b32 s17, s22, s17
	v_cndmask_b32_e32 v75, v203, v75, vcc
	v_lshl_or_b32 v138, v74, 3, s17
	v_lshlrev_b32_e32 v165, 2, v75
	v_xor_b32_e32 v75, 32, v203
	v_and_b32_e32 v64, 15, v164
	s_add_i32 s40, s11, s51
	v_cmp_lt_i32_e32 vcc, v75, v76
	v_ashrrev_i32_e32 v139, 31, v138
	v_or_b32_e32 v158, s40, v64
	v_cndmask_b32_e32 v75, v203, v75, vcc
	v_lshlrev_b64 v[142:143], 2, v[138:139]
	v_lshlrev_b32_e32 v166, 2, v75
	v_cmp_eq_u32_e32 vcc, 0, v74
	v_ashrrev_i32_e32 v159, 31, v158
	v_lshl_add_u64 v[74:75], s[2:3], 0, v[142:143]
	s_mov_b64 s[2:3], 0x5000
	v_lshlrev_b64 v[140:141], 12, v[158:159]
	v_lshl_add_u64 v[152:153], v[74:75], 0, s[2:3]
	s_movk_i32 s2, 0x5000
	v_add_co_u32_e64 v74, s[40:41], s2, v74
	v_lshl_add_u64 v[140:141], s[0:1], 0, v[140:141]
	s_nop 0
	v_addc_co_u32_e64 v75, s[40:41], 0, v75, s[40:41]
	v_lshl_add_u64 v[140:141], v[140:141], 0, v[142:143]
	global_load_dwordx4 v[78:81], v[74:75], off
	s_nop 0
	global_load_dwordx4 v[74:77], v[152:153], off offset:16
	v_mov_b32_e32 v218, v140
	v_mov_b32_e32 v219, v141
	global_load_dwordx4 v[148:151], v[140:141], off offset:16
	global_load_dwordx4 v[144:147], v[140:141], off
	v_or_b32_e32 v64, s51, v64
	s_waitcnt vmcnt(1)
	v_pk_fma_f32 v[148:149], v[56:57], v[74:75], v[148:149]
	s_waitcnt vmcnt(0)
	v_pk_fma_f32 v[142:143], v[72:73], v[80:81], v[146:147]
	v_pk_fma_f32 v[144:145], v[70:71], v[78:79], v[144:145]
	v_pk_fma_f32 v[146:147], v[58:59], v[76:77], v[150:151]
	v_mul_f32_e32 v70, v145, v145
	v_mul_f32_e32 v71, v143, v143
	v_mul_f32_e32 v56, v149, v149
	v_mul_f32_e32 v57, v147, v147
	v_fmac_f32_e32 v70, v144, v144
	v_fmac_f32_e32 v71, v142, v142
	v_fmac_f32_e32 v56, v148, v148
	v_fmac_f32_e32 v57, v146, v146
	v_add_f32_e32 v70, v70, v71
	v_add_f32_e32 v56, v56, v57
	v_add_f32_e32 v159, v70, v56
	global_load_dwordx4 v[56:59], v[152:153], off offset:528
	global_load_dwordx4 v[70:73], v[152:153], off offset:512
	s_nop 0
	global_load_dwordx4 v[150:153], v[140:141], off offset:528
	global_load_dwordx4 v[154:157], v[140:141], off offset:512
	s_mov_b64 s[98:99], 0x10000
	v_lshl_add_u64 v[220:221], v[218:219], 0, s[98:99]
	global_load_dwordx4 v[224:227], v[220:221], off
	global_load_dwordx4 v[220:223], v[220:221], off offset:16
	s_mov_b64 s[98:99], 0x10000
	v_lshl_add_u64 v[228:229], v[218:219], 0, s[98:99]
	global_load_dwordx4 v[232:235], v[228:229], off offset:512
	global_load_dwordx4 v[228:231], v[228:229], off offset:528
	s_mov_b64 s[98:99], 0x20000
	v_lshl_add_u64 v[236:237], v[218:219], 0, s[98:99]
	global_load_dwordx4 v[240:243], v[236:237], off
	global_load_dwordx4 v[236:239], v[236:237], off offset:16
	s_waitcnt vmcnt(7)
	v_pk_fma_f32 v[132:133], v[132:133], v[58:59], v[152:153]
	s_waitcnt vmcnt(6)
	v_pk_fma_f32 v[136:137], v[136:137], v[72:73], v[156:157]
	v_pk_fma_f32 v[134:135], v[134:135], v[70:71], v[154:155]
	v_mul_f32_e32 v155, v137, v137
	v_mul_f32_e32 v154, v135, v135
	v_pk_fma_f32 v[130:131], v[130:131], v[56:57], v[150:151]
	v_fmac_f32_e32 v154, v134, v134
	v_fmac_f32_e32 v155, v136, v136
	v_mul_f32_e32 v150, v131, v131
	v_mul_f32_e32 v151, v133, v133
	v_add_f32_e32 v154, v154, v155
	v_fmac_f32_e32 v150, v130, v130
	v_fmac_f32_e32 v151, v132, v132
	v_add_f32_e32 v154, v159, v154
	v_add_f32_e32 v150, v150, v151
	v_add_f32_e32 v150, v154, v150
	ds_bpermute_b32 v151, v165, v150
	s_waitcnt lgkmcnt(0)
	v_add_f32_e32 v150, v150, v151
	ds_bpermute_b32 v151, v166, v150
	s_and_saveexec_b64 s[2:3], vcc
	v_readlane_b32 s92, v253, 55
	v_readlane_b32 s93, v253, 60
	s_cbranch_execz .LBB0_38
	s_lshl_b32 s17, s10, 2
	s_add_i32 s17, s17, 0
	v_lshl_add_u32 v152, v64, 4, s17
	s_waitcnt lgkmcnt(0)
	v_add_f32_e32 v150, v150, v151
	ds_write_b32 v152, v150
.LBB0_38:
	s_or_b64 exec, exec, s[2:3]
	v_or_b32_e32 v150, 16, v158
	s_waitcnt lgkmcnt(0)
	v_ashrrev_i32_e32 v151, 31, v150
	v_lshlrev_b64 v[150:151], 12, v[150:151]
	v_lshl_add_u64 v[150:151], s[0:1], 0, v[150:151]
	v_lshl_add_u64 v[150:151], v[138:139], 2, v[150:151]
	s_waitcnt vmcnt(4)
	v_pk_fma_f32 v[124:125], v[124:125], v[76:77], v[222:223]
	s_waitcnt vmcnt(4)
	v_pk_fma_f32 v[128:129], v[128:129], v[80:81], v[226:227]
	v_pk_fma_f32 v[126:127], v[126:127], v[78:79], v[224:225]
	v_pk_fma_f32 v[122:123], v[122:123], v[74:75], v[220:221]
	s_mov_b64 s[98:99], 0x20000
	v_lshl_add_u64 v[220:221], v[218:219], 0, s[98:99]
	global_load_dwordx4 v[224:227], v[220:221], off offset:512
	global_load_dwordx4 v[220:223], v[220:221], off offset:528
	v_mul_f32_e32 v156, v127, v127
	v_mul_f32_e32 v157, v129, v129
	v_mul_f32_e32 v152, v123, v123
	v_mul_f32_e32 v153, v125, v125
	v_fmac_f32_e32 v156, v126, v126
	v_fmac_f32_e32 v157, v128, v128
	v_fmac_f32_e32 v152, v122, v122
	v_fmac_f32_e32 v153, v124, v124
	v_add_f32_e32 v156, v156, v157
	v_add_f32_e32 v152, v152, v153
	v_add_f32_e32 v152, v156, v152
	s_waitcnt vmcnt(4)
	v_pk_fma_f32 v[154:155], v[114:115], v[56:57], v[228:229]
	s_waitcnt vmcnt(4)
	v_pk_fma_f32 v[120:121], v[120:121], v[72:73], v[234:235]
	v_pk_fma_f32 v[118:119], v[118:119], v[70:71], v[232:233]
	v_mul_f32_e32 v159, v121, v121
	v_mul_f32_e32 v153, v119, v119
	v_fmac_f32_e32 v153, v118, v118
	v_fmac_f32_e32 v159, v120, v120
	v_add_f32_e32 v153, v153, v159
	v_add_f32_e32 v159, v152, v153
	v_pk_fma_f32 v[152:153], v[116:117], v[58:59], v[230:231]
	s_mov_b64 s[98:99], 0x30000
	v_lshl_add_u64 v[228:229], v[218:219], 0, s[98:99]
	global_load_dwordx4 v[232:235], v[228:229], off
	global_load_dwordx4 v[228:231], v[228:229], off offset:16
	v_mul_f32_e32 v114, v155, v155
	v_mul_f32_e32 v115, v153, v153
	v_fmac_f32_e32 v114, v154, v154
	v_fmac_f32_e32 v115, v152, v152
	v_add_f32_e32 v114, v114, v115
	v_add_f32_e32 v114, v159, v114
	ds_bpermute_b32 v115, v165, v114
	s_waitcnt lgkmcnt(0)
	v_add_f32_e32 v114, v114, v115
	ds_bpermute_b32 v115, v166, v114
	s_and_saveexec_b64 s[2:3], vcc
	s_cbranch_execz .LBB0_40
	s_lshl_b32 s17, s10, 2
	s_add_i32 s17, s17, 0
	v_lshl_add_u32 v116, v64, 4, s17
	s_waitcnt lgkmcnt(0)
	v_add_f32_e32 v114, v114, v115
	ds_write_b32 v116, v114 offset:256
.LBB0_40:
	s_or_b64 exec, exec, s[2:3]
	v_or_b32_e32 v114, 32, v158
	s_waitcnt lgkmcnt(0)
	v_ashrrev_i32_e32 v115, 31, v114
	v_lshlrev_b64 v[114:115], 12, v[114:115]
	v_lshl_add_u64 v[114:115], s[0:1], 0, v[114:115]
	v_lshl_add_u64 v[114:115], v[138:139], 2, v[114:115]
	s_waitcnt vmcnt(4)
	v_pk_fma_f32 v[108:109], v[108:109], v[76:77], v[238:239]
	s_waitcnt vmcnt(4)
	v_pk_fma_f32 v[112:113], v[112:113], v[80:81], v[242:243]
	v_pk_fma_f32 v[110:111], v[110:111], v[78:79], v[240:241]
	v_pk_fma_f32 v[106:107], v[106:107], v[74:75], v[236:237]
	s_mov_b64 s[98:99], 0x30000
	v_lshl_add_u64 v[236:237], v[218:219], 0, s[98:99]
	global_load_dwordx4 v[240:243], v[236:237], off offset:512
	global_load_dwordx4 v[236:239], v[236:237], off offset:528
	v_mul_f32_e32 v116, v111, v111
	v_mul_f32_e32 v117, v113, v113
	v_fmac_f32_e32 v116, v110, v110
	v_fmac_f32_e32 v117, v112, v112
	v_add_f32_e32 v116, v116, v117
	v_mul_f32_e32 v117, v107, v107
	v_mul_f32_e32 v156, v109, v109
	v_fmac_f32_e32 v117, v106, v106
	v_fmac_f32_e32 v156, v108, v108
	v_add_f32_e32 v117, v117, v156
	v_add_f32_e32 v116, v116, v117
	s_waitcnt vmcnt(4)
	v_pk_fma_f32 v[100:101], v[100:101], v[58:59], v[222:223]
	s_waitcnt vmcnt(4)
	v_pk_fma_f32 v[104:105], v[104:105], v[72:73], v[226:227]
	v_pk_fma_f32 v[102:103], v[102:103], v[70:71], v[224:225]
	v_mul_f32_e32 v156, v105, v105
	v_mul_f32_e32 v117, v103, v103
	v_fmac_f32_e32 v117, v102, v102
	v_fmac_f32_e32 v156, v104, v104
	v_add_f32_e32 v117, v117, v156
	v_add_f32_e32 v156, v116, v117
	v_pk_fma_f32 v[116:117], v[98:99], v[56:57], v[220:221]
	s_mov_b64 s[98:99], 0x80000
	v_lshl_add_u64 v[220:221], v[218:219], 0, s[98:99]
	global_load_dwordx4 v[224:227], v[220:221], off
	global_load_dwordx4 v[220:223], v[220:221], off offset:16
	v_mul_f32_e32 v99, v101, v101
	v_mul_f32_e32 v98, v117, v117
	v_fmac_f32_e32 v98, v116, v116
	v_fmac_f32_e32 v99, v100, v100
	v_add_f32_e32 v98, v98, v99
	v_add_f32_e32 v98, v156, v98
	ds_bpermute_b32 v99, v165, v98
	s_waitcnt lgkmcnt(0)
	v_add_f32_e32 v98, v98, v99
	ds_bpermute_b32 v99, v166, v98
	s_and_saveexec_b64 s[2:3], vcc
	s_cbranch_execz .LBB0_42
	s_lshl_b32 s17, s10, 2
	s_add_i32 s17, s17, 0
	v_lshl_add_u32 v156, v64, 4, s17
	s_waitcnt lgkmcnt(0)
	v_add_f32_e32 v98, v98, v99
	ds_write_b32 v156, v98 offset:512
.LBB0_42:
	s_or_b64 exec, exec, s[2:3]
	v_or_b32_e32 v98, 48, v158
	s_waitcnt lgkmcnt(0)
	v_ashrrev_i32_e32 v99, 31, v98
	v_lshlrev_b64 v[98:99], 12, v[98:99]
	v_lshl_add_u64 v[98:99], s[0:1], 0, v[98:99]
	v_lshl_add_u64 v[98:99], v[138:139], 2, v[98:99]
	s_waitcnt vmcnt(4)
	v_pk_fma_f32 v[92:93], v[92:93], v[76:77], v[230:231]
	s_waitcnt vmcnt(4)
	v_pk_fma_f32 v[96:97], v[96:97], v[80:81], v[234:235]
	v_pk_fma_f32 v[156:157], v[94:95], v[78:79], v[232:233]
	v_mul_f32_e32 v95, v97, v97
	v_mul_f32_e32 v94, v157, v157
	v_fmac_f32_e32 v94, v156, v156
	v_fmac_f32_e32 v95, v96, v96
	v_add_f32_e32 v159, v94, v95
	v_pk_fma_f32 v[94:95], v[90:91], v[74:75], v[228:229]
	s_mov_b64 s[98:99], 0x80000
	v_lshl_add_u64 v[228:229], v[218:219], 0, s[98:99]
	global_load_dwordx4 v[232:235], v[228:229], off offset:512
	global_load_dwordx4 v[228:231], v[228:229], off offset:528
	v_mul_f32_e32 v90, v95, v95
	v_mul_f32_e32 v91, v93, v93
	v_fmac_f32_e32 v90, v94, v94
	v_fmac_f32_e32 v91, v92, v92
	v_add_f32_e32 v90, v90, v91
	v_add_f32_e32 v90, v159, v90
	s_waitcnt vmcnt(4)
	v_pk_fma_f32 v[84:85], v[84:85], v[58:59], v[238:239]
	s_waitcnt vmcnt(4)
	v_pk_fma_f32 v[88:89], v[88:89], v[72:73], v[242:243]
	v_pk_fma_f32 v[86:87], v[86:87], v[70:71], v[240:241]
	v_mul_f32_e32 v159, v89, v89
	v_mul_f32_e32 v91, v87, v87
	v_fmac_f32_e32 v91, v86, v86
	v_fmac_f32_e32 v159, v88, v88
	v_add_f32_e32 v91, v91, v159
	v_pk_fma_f32 v[82:83], v[82:83], v[56:57], v[236:237]
	s_mov_b64 s[98:99], 0x90000
	v_lshl_add_u64 v[236:237], v[218:219], 0, s[98:99]
	global_load_dwordx4 v[240:243], v[236:237], off
	global_load_dwordx4 v[236:239], v[236:237], off offset:16
	v_add_f32_e32 v90, v90, v91
	v_mul_f32_e32 v91, v83, v83
	v_mul_f32_e32 v159, v85, v85
	v_fmac_f32_e32 v91, v82, v82
	v_fmac_f32_e32 v159, v84, v84
	v_add_f32_e32 v91, v91, v159
	v_add_f32_e32 v90, v90, v91
	ds_bpermute_b32 v91, v165, v90
	s_waitcnt lgkmcnt(0)
	v_add_f32_e32 v90, v90, v91
	ds_bpermute_b32 v91, v166, v90
	s_and_saveexec_b64 s[2:3], vcc
	s_cbranch_execz .LBB0_44
	s_lshl_b32 s17, s10, 2
	s_add_i32 s17, s17, 0
	v_lshl_add_u32 v159, v64, 4, s17
	s_waitcnt lgkmcnt(0)
	v_add_f32_e32 v90, v90, v91
	ds_write_b32 v159, v90 offset:768
.LBB0_44:
	s_or_b64 exec, exec, s[2:3]
	v_add_u32_e32 v90, 0x80, v158
	s_waitcnt lgkmcnt(0)
	v_ashrrev_i32_e32 v91, 31, v90
	v_lshlrev_b64 v[90:91], 12, v[90:91]
	v_lshl_add_u64 v[90:91], s[0:1], 0, v[90:91]
	v_lshl_add_u64 v[90:91], v[138:139], 2, v[90:91]
	s_waitcnt vmcnt(4)
	v_pk_fma_f32 v[62:63], v[62:63], v[76:77], v[222:223]
	s_waitcnt vmcnt(4)
	v_pk_fma_f32 v[68:69], v[68:69], v[80:81], v[226:227]
	v_pk_fma_f32 v[66:67], v[66:67], v[78:79], v[224:225]
	v_pk_fma_f32 v[60:61], v[60:61], v[74:75], v[220:221]
	s_mov_b64 s[98:99], 0x90000
	v_lshl_add_u64 v[220:221], v[218:219], 0, s[98:99]
	global_load_dwordx4 v[224:227], v[220:221], off offset:512
	global_load_dwordx4 v[220:223], v[220:221], off offset:528
	v_mul_f32_e32 v159, v67, v67
	v_mul_f32_e32 v167, v69, v69
	v_mul_f32_e32 v160, v61, v61
	v_mul_f32_e32 v161, v63, v63
	v_fmac_f32_e32 v159, v66, v66
	v_fmac_f32_e32 v167, v68, v68
	v_fmac_f32_e32 v160, v60, v60
	v_fmac_f32_e32 v161, v62, v62
	v_add_f32_e32 v159, v159, v167
	v_add_f32_e32 v160, v160, v161
	v_add_f32_e32 v159, v159, v160
	s_waitcnt vmcnt(4)
	v_pk_fma_f32 v[50:51], v[50:51], v[58:59], v[230:231]
	s_waitcnt vmcnt(4)
	v_pk_fma_f32 v[54:55], v[54:55], v[72:73], v[234:235]
	v_pk_fma_f32 v[52:53], v[52:53], v[70:71], v[232:233]
	v_mul_f32_e32 v168, v55, v55
	v_mul_f32_e32 v167, v53, v53
	v_pk_fma_f32 v[48:49], v[48:49], v[56:57], v[228:229]
	s_mov_b64 s[98:99], 0xa0000
	v_lshl_add_u64 v[228:229], v[218:219], 0, s[98:99]
	global_load_dwordx4 v[232:235], v[228:229], off
	global_load_dwordx4 v[228:231], v[228:229], off offset:16
	v_fmac_f32_e32 v167, v52, v52
	v_fmac_f32_e32 v168, v54, v54
	v_mul_f32_e32 v160, v49, v49
	v_mul_f32_e32 v161, v51, v51
	v_add_f32_e32 v167, v167, v168
	v_fmac_f32_e32 v160, v48, v48
	v_fmac_f32_e32 v161, v50, v50
	v_add_f32_e32 v159, v159, v167
	v_add_f32_e32 v160, v160, v161
	v_add_f32_e32 v159, v159, v160
	ds_bpermute_b32 v160, v165, v159
	s_waitcnt lgkmcnt(0)
	v_add_f32_e32 v159, v159, v160
	ds_bpermute_b32 v160, v166, v159
	s_and_saveexec_b64 s[2:3], vcc
	s_cbranch_execz .LBB0_46
	s_lshl_b32 s17, s10, 2
	s_add_i32 s17, s17, 0
	v_lshl_add_u32 v161, v64, 4, s17
	s_waitcnt lgkmcnt(0)
	v_add_f32_e32 v159, v159, v160
	ds_write_b32 v161, v159 offset:2048
.LBB0_46:
	s_or_b64 exec, exec, s[2:3]
	s_waitcnt lgkmcnt(0)
	v_add_u32_e32 v160, 0x90, v158
	v_ashrrev_i32_e32 v161, 31, v160
	v_lshlrev_b64 v[160:161], 12, v[160:161]
	v_lshl_add_u64 v[160:161], s[0:1], 0, v[160:161]
	v_lshl_add_u64 v[160:161], v[138:139], 2, v[160:161]
	s_waitcnt vmcnt(4)
	v_pk_fma_f32 v[42:43], v[42:43], v[76:77], v[238:239]
	s_waitcnt vmcnt(4)
	v_pk_fma_f32 v[46:47], v[46:47], v[80:81], v[242:243]
	v_pk_fma_f32 v[44:45], v[44:45], v[78:79], v[240:241]
	v_pk_fma_f32 v[40:41], v[40:41], v[74:75], v[236:237]
	s_mov_b64 s[98:99], 0xa0000
	v_lshl_add_u64 v[236:237], v[218:219], 0, s[98:99]
	global_load_dwordx4 v[240:243], v[236:237], off offset:512
	global_load_dwordx4 v[236:239], v[236:237], off offset:528
	v_mul_f32_e32 v159, v45, v45
	v_mul_f32_e32 v162, v47, v47
	v_fmac_f32_e32 v159, v44, v44
	v_fmac_f32_e32 v162, v46, v46
	v_add_f32_e32 v159, v159, v162
	v_mul_f32_e32 v162, v41, v41
	v_mul_f32_e32 v163, v43, v43
	v_fmac_f32_e32 v162, v40, v40
	v_fmac_f32_e32 v163, v42, v42
	v_add_f32_e32 v162, v162, v163
	v_add_f32_e32 v159, v159, v162
	s_waitcnt vmcnt(4)
	v_pk_fma_f32 v[34:35], v[34:35], v[58:59], v[222:223]
	s_waitcnt vmcnt(4)
	v_pk_fma_f32 v[38:39], v[38:39], v[72:73], v[226:227]
	v_pk_fma_f32 v[36:37], v[36:37], v[70:71], v[224:225]
	v_mul_f32_e32 v163, v39, v39
	v_mul_f32_e32 v162, v37, v37
	v_fmac_f32_e32 v162, v36, v36
	v_fmac_f32_e32 v163, v38, v38
	v_add_f32_e32 v162, v162, v163
	v_pk_fma_f32 v[32:33], v[32:33], v[56:57], v[220:221]
	s_mov_b64 s[98:99], 0xb0000
	v_lshl_add_u64 v[220:221], v[218:219], 0, s[98:99]
	global_load_dwordx4 v[224:227], v[220:221], off
	global_load_dwordx4 v[220:223], v[220:221], off offset:16
	v_add_f32_e32 v159, v159, v162
	v_mul_f32_e32 v162, v33, v33
	v_mul_f32_e32 v163, v35, v35
	v_fmac_f32_e32 v162, v32, v32
	v_fmac_f32_e32 v163, v34, v34
	v_add_f32_e32 v162, v162, v163
	v_add_f32_e32 v159, v159, v162
	ds_bpermute_b32 v162, v165, v159
	s_waitcnt lgkmcnt(0)
	v_add_f32_e32 v159, v159, v162
	ds_bpermute_b32 v162, v166, v159
	s_and_saveexec_b64 s[2:3], vcc
	s_cbranch_execz .LBB0_48
	s_lshl_b32 s17, s10, 2
	s_add_i32 s17, s17, 0
	v_lshl_add_u32 v163, v64, 4, s17
	s_waitcnt lgkmcnt(0)
	v_add_f32_e32 v159, v159, v162
	ds_write_b32 v163, v159 offset:2304
.LBB0_48:
	s_or_b64 exec, exec, s[2:3]
	s_waitcnt lgkmcnt(0)
	v_add_u32_e32 v162, 0xa0, v158
	v_ashrrev_i32_e32 v163, 31, v162
	v_lshlrev_b64 v[162:163], 12, v[162:163]
	v_lshl_add_u64 v[162:163], s[0:1], 0, v[162:163]
	v_lshl_add_u64 v[162:163], v[138:139], 2, v[162:163]
	s_waitcnt vmcnt(4)
	v_pk_fma_f32 v[26:27], v[26:27], v[76:77], v[230:231]
	s_waitcnt vmcnt(4)
	v_pk_fma_f32 v[30:31], v[30:31], v[80:81], v[234:235]
	v_pk_fma_f32 v[28:29], v[28:29], v[78:79], v[232:233]
	v_mul_f32_e32 v167, v31, v31
	v_mul_f32_e32 v159, v29, v29
	v_fmac_f32_e32 v159, v28, v28
	v_fmac_f32_e32 v167, v30, v30
	v_pk_fma_f32 v[24:25], v[24:25], v[74:75], v[228:229]
	s_mov_b64 s[98:99], 0xb0000
	v_lshl_add_u64 v[228:229], v[218:219], 0, s[98:99]
	global_load_dwordx4 v[232:235], v[228:229], off offset:512
	global_load_dwordx4 v[228:231], v[228:229], off offset:528
	v_add_f32_e32 v159, v159, v167
	v_mul_f32_e32 v167, v25, v25
	v_mul_f32_e32 v168, v27, v27
	v_fmac_f32_e32 v167, v24, v24
	v_fmac_f32_e32 v168, v26, v26
	v_add_f32_e32 v167, v167, v168
	v_add_f32_e32 v159, v159, v167
	s_waitcnt vmcnt(4)
	v_pk_fma_f32 v[18:19], v[18:19], v[58:59], v[238:239]
	s_waitcnt vmcnt(4)
	v_pk_fma_f32 v[22:23], v[22:23], v[72:73], v[242:243]
	v_pk_fma_f32 v[20:21], v[20:21], v[70:71], v[240:241]
	v_mul_f32_e32 v172, v23, v23
	v_mul_f32_e32 v167, v21, v21
	v_fmac_f32_e32 v167, v20, v20
	v_fmac_f32_e32 v172, v22, v22
	v_add_f32_e32 v167, v167, v172
	v_pk_fma_f32 v[16:17], v[16:17], v[56:57], v[236:237]
	v_add_f32_e32 v159, v159, v167
	v_mul_f32_e32 v167, v17, v17
	v_mul_f32_e32 v168, v19, v19
	v_fmac_f32_e32 v167, v16, v16
	v_fmac_f32_e32 v168, v18, v18
	v_add_f32_e32 v167, v167, v168
	v_add_f32_e32 v159, v159, v167
	ds_bpermute_b32 v167, v165, v159
	s_waitcnt lgkmcnt(0)
	v_add_f32_e32 v159, v159, v167
	ds_bpermute_b32 v167, v166, v159
	s_and_saveexec_b64 s[2:3], vcc
	s_cbranch_execz .LBB0_50
	s_lshl_b32 s17, s10, 2
	s_add_i32 s17, s17, 0
	v_lshl_add_u32 v168, v64, 4, s17
	s_waitcnt lgkmcnt(0)
	v_add_f32_e32 v159, v159, v167
	ds_write_b32 v168, v159 offset:2560
.LBB0_50:
	s_or_b64 exec, exec, s[2:3]
	v_add_u32_e32 v158, 0xb0, v158
	v_ashrrev_i32_e32 v159, 31, v158
	v_lshlrev_b64 v[158:159], 12, v[158:159]
	v_lshl_add_u64 v[158:159], s[0:1], 0, v[158:159]
	v_lshl_add_u64 v[158:159], v[138:139], 2, v[158:159]
	s_waitcnt vmcnt(2)
	v_pk_fma_f32 v[76:77], v[10:11], v[76:77], v[222:223]
	s_waitcnt vmcnt(2)
	v_pk_fma_f32 v[80:81], v[14:15], v[80:81], v[226:227]
	v_pk_fma_f32 v[78:79], v[12:13], v[78:79], v[224:225]
	v_pk_fma_f32 v[74:75], v[8:9], v[74:75], v[220:221]
	v_mul_f32_e32 v12, v79, v79
	v_mul_f32_e32 v13, v81, v81
	v_mul_f32_e32 v8, v75, v75
	v_mul_f32_e32 v9, v77, v77
	v_fmac_f32_e32 v12, v78, v78
	v_fmac_f32_e32 v13, v80, v80
	v_fmac_f32_e32 v8, v74, v74
	v_fmac_f32_e32 v9, v76, v76
	v_add_f32_e32 v12, v12, v13
	v_add_f32_e32 v8, v8, v9
	s_waitcnt lgkmcnt(0)
	v_add_f32_e32 v167, v12, v8
	s_waitcnt vmcnt(0)
	v_pk_fma_f32 v[58:59], v[2:3], v[58:59], v[230:231]
	s_waitcnt vmcnt(0)
	v_pk_fma_f32 v[72:73], v[6:7], v[72:73], v[234:235]
	v_pk_fma_f32 v[70:71], v[4:5], v[70:71], v[232:233]
	v_mul_f32_e32 v5, v73, v73
	v_mul_f32_e32 v4, v71, v71
	v_pk_fma_f32 v[56:57], v[0:1], v[56:57], v[228:229]
	v_fmac_f32_e32 v4, v70, v70
	v_fmac_f32_e32 v5, v72, v72
	v_mul_f32_e32 v0, v57, v57
	v_mul_f32_e32 v1, v59, v59
	v_add_f32_e32 v4, v4, v5
	v_fmac_f32_e32 v0, v56, v56
	v_fmac_f32_e32 v1, v58, v58
	v_add_f32_e32 v4, v167, v4
	v_add_f32_e32 v0, v0, v1
	v_add_f32_e32 v0, v4, v0
	ds_bpermute_b32 v1, v165, v0
	s_waitcnt lgkmcnt(0)
	v_add_f32_e32 v0, v0, v1
	ds_bpermute_b32 v1, v166, v0
	s_and_saveexec_b64 s[2:3], vcc
	s_cbranch_execz .LBB0_52
	s_lshl_b32 s10, s10, 2
	s_add_i32 s10, s10, 0
	s_waitcnt lgkmcnt(0)
	v_add_f32_e32 v0, v0, v1
	v_lshl_add_u32 v1, v64, 4, s10
	ds_write_b32 v1, v0 offset:2816

.LBB0_98:
	s_lshl_b32 s7, s6, 5
	v_readlane_b32 s52, v253, 63
	v_readlane_b32 s2, v254, 43
	v_readlane_b32 s53, v254, 0
	v_readlane_b32 s3, v254, 44
	s_add_u32 s2, s52, s2
	s_addc_u32 s3, s53, s3
	s_add_i32 s10, s14, 7
	s_cmp_lt_u32 s10, 19
	s_cselect_b32 s85, s3, s1
	s_cselect_b32 s84, s2, s0
	s_ashr_i32 s2, s40, 4
	s_mul_hi_i32 s3, s2, 0x1800
	s_mulk_i32 s2, 0x1800
	s_lshl_b32 s10, s40, 8
	s_lshl_b32 s46, s80, 8
	s_lshl_b64 s[82:83], s[2:3], 2
	v_readlane_b32 s2, v254, 41
	v_mov_b32_e32 v182, v203
	v_readlane_b32 s3, v254, 42
	s_add_u32 s2, s2, s82
	s_waitcnt vmcnt(0)
	s_barrier
	s_waitcnt vmcnt(0)
	s_barrier
	s_addc_u32 s3, s3, s83
	v_and_b32_e32 v168, 15, v182
	v_bfe_u32 v169, v182, 4, 2
	s_add_i32 s17, s10, s11
	v_or_b32_e32 v152, s17, v168
	v_lshlrev_b32_e32 v64, 3, v169
	s_or_b32 s17, s46, s7
	v_or_b32_e32 v176, s17, v64
	v_ashrrev_i32_e32 v177, 31, v176
	v_lshlrev_b64 v[146:147], 2, v[176:177]
	v_lshl_add_u64 v[130:131], s[2:3], 0, v[146:147]
	s_movk_i32 s2, 0x2000
	v_ashrrev_i32_e32 v153, 31, v152
	v_add_co_u32_e32 v132, vcc, s2, v130
	v_lshlrev_b64 v[154:155], 12, v[152:153]
	s_nop 0
	v_addc_co_u32_e32 v133, vcc, 0, v131, vcc
	global_load_dwordx4 v[138:141], v[132:133], off
	v_lshl_add_u64 v[132:133], s[84:85], 0, v[154:155]
	v_lshl_add_u64 v[132:133], v[132:133], 0, v[146:147]
	v_mov_b32_e32 v218, v132
	v_mov_b32_e32 v219, v133
	global_load_dwordx4 v[148:151], v[132:133], off offset:16
	global_load_dwordx4 v[156:159], v[132:133], off
	s_mov_b64 s[2:3], 0x2000
	v_lshl_add_u64 v[130:131], v[130:131], 0, s[2:3]
	global_load_dwordx4 v[142:145], v[130:131], off offset:16
	global_load_dwordx4 v[134:137], v[130:131], off offset:512
	global_load_dwordx4 v[160:163], v[132:133], off offset:512
	global_load_dwordx4 v[164:167], v[132:133], off offset:528
	s_nop 0
	global_load_dwordx4 v[130:133], v[130:131], off offset:528
	s_mov_b64 s[98:99], 0x10000
	v_lshl_add_u64 v[220:221], v[218:219], 0, s[98:99]
	global_load_dwordx4 v[224:227], v[220:221], off
	global_load_dwordx4 v[220:223], v[220:221], off offset:16
	s_mov_b64 s[98:99], 0x10000
	v_lshl_add_u64 v[228:229], v[218:219], 0, s[98:99]
	global_load_dwordx4 v[232:235], v[228:229], off offset:512
	global_load_dwordx4 v[228:231], v[228:229], off offset:528
	s_mov_b64 s[98:99], 0x20000
	v_lshl_add_u64 v[236:237], v[218:219], 0, s[98:99]
	global_load_dwordx4 v[240:243], v[236:237], off
	global_load_dwordx4 v[236:239], v[236:237], off offset:16
	v_and_b32_e32 v171, 64, v203
	v_xor_b32_e32 v170, 16, v203
	v_add_u32_e32 v171, 64, v171
	v_cmp_lt_i32_e32 vcc, v170, v171
	v_or_b32_e32 v198, s11, v168
	v_readlane_b32 s54, v254, 1
	v_cndmask_b32_e32 v170, v203, v170, vcc
	v_lshlrev_b32_e32 v183, 2, v170
	v_readlane_b32 s55, v254, 2
	v_readlane_b32 s56, v254, 3
	v_readlane_b32 s57, v254, 4
	v_readlane_b32 s58, v254, 5
	v_readlane_b32 s59, v254, 6
	v_readlane_b32 s60, v254, 7
	v_readlane_b32 s61, v254, 8
	v_readlane_b32 s62, v254, 9
	v_readlane_b32 s63, v254, 10
	v_readlane_b32 s64, v254, 11
	v_readlane_b32 s65, v254, 12
	v_readlane_b32 s66, v254, 13
	v_readlane_b32 s67, v254, 14
	s_waitcnt vmcnt(10)
	v_pk_fma_f32 v[50:51], v[50:51], v[144:145], v[150:151]
	v_pk_fma_f32 v[54:55], v[54:55], v[140:141], v[158:159]
	v_pk_fma_f32 v[52:53], v[52:53], v[138:139], v[156:157]
	v_pk_fma_f32 v[48:49], v[48:49], v[142:143], v[148:149]
	s_waitcnt vmcnt(8)
	v_pk_fma_f32 v[26:27], v[26:27], v[136:137], v[162:163]
	v_pk_fma_f32 v[24:25], v[24:25], v[134:135], v[160:161]
	v_mul_f32_e32 v148, v53, v53
	v_mul_f32_e32 v149, v55, v55
	v_mul_f32_e32 v150, v49, v49
	v_mul_f32_e32 v151, v51, v51
	s_waitcnt vmcnt(6)
	v_pk_fma_f32 v[22:23], v[22:23], v[132:133], v[166:167]
	v_pk_fma_f32 v[20:21], v[20:21], v[130:131], v[164:165]
	v_mul_f32_e32 v156, v25, v25
	v_mul_f32_e32 v157, v27, v27
	v_fmac_f32_e32 v148, v52, v52
	v_fmac_f32_e32 v149, v54, v54
	v_fmac_f32_e32 v150, v48, v48
	v_fmac_f32_e32 v151, v50, v50
	v_mul_f32_e32 v158, v21, v21
	v_mul_f32_e32 v159, v23, v23
	v_fmac_f32_e32 v156, v24, v24
	v_fmac_f32_e32 v157, v26, v26
	v_add_f32_e32 v148, v148, v149
	v_add_f32_e32 v149, v150, v151
	v_fmac_f32_e32 v158, v20, v20
	v_fmac_f32_e32 v159, v22, v22
	v_add_f32_e32 v150, v156, v157
	v_add_f32_e32 v148, v148, v149
	v_add_f32_e32 v148, v148, v150
	v_add_f32_e32 v149, v158, v159
	v_add_f32_e32 v148, v148, v149
	ds_bpermute_b32 v149, v183, v148
	v_xor_b32_e32 v150, 32, v203
	v_cmp_lt_i32_e32 vcc, v150, v171
	s_waitcnt lgkmcnt(0)
	v_add_f32_e32 v148, v148, v149
	v_cndmask_b32_e32 v150, v203, v150, vcc
	v_lshlrev_b32_e32 v184, 2, v150
	ds_bpermute_b32 v149, v184, v148
	v_cmp_eq_u32_e32 vcc, 0, v169
	s_and_saveexec_b64 s[2:3], vcc
	s_cbranch_execz .LBB0_100
	s_lshl_b32 s11, s6, 2
	s_add_i32 s11, s11, 0
	v_lshl_add_u32 v150, v198, 4, s11
	s_waitcnt lgkmcnt(0)
	v_add_f32_e32 v148, v148, v149
	ds_write_b32 v150, v148
.LBB0_100:
	s_or_b64 exec, exec, s[2:3]
	v_or_b32_e32 v148, 16, v152
	s_waitcnt lgkmcnt(0)
	v_ashrrev_i32_e32 v149, 31, v148
	v_lshlrev_b64 v[150:151], 12, v[148:149]
	v_lshl_add_u64 v[156:157], s[84:85], 0, v[150:151]
	v_lshl_add_u64 v[164:165], v[176:177], 2, v[156:157]
	s_waitcnt vmcnt(4)
	v_pk_fma_f32 v[2:3], v[2:3], v[144:145], v[222:223]
	s_waitcnt vmcnt(4)
	v_pk_fma_f32 v[6:7], v[6:7], v[140:141], v[226:227]
	v_pk_fma_f32 v[4:5], v[4:5], v[138:139], v[224:225]
	v_pk_fma_f32 v[0:1], v[0:1], v[142:143], v[220:221]
	s_mov_b64 s[98:99], 0x20000
	v_lshl_add_u64 v[220:221], v[218:219], 0, s[98:99]
	global_load_dwordx4 v[224:227], v[220:221], off offset:512
	global_load_dwordx4 v[220:223], v[220:221], off offset:528
	v_mul_f32_e32 v160, v5, v5
	v_mul_f32_e32 v161, v7, v7
	v_mul_f32_e32 v156, v1, v1
	v_mul_f32_e32 v157, v3, v3
	v_fmac_f32_e32 v160, v4, v4
	v_fmac_f32_e32 v161, v6, v6
	v_fmac_f32_e32 v156, v0, v0
	v_fmac_f32_e32 v157, v2, v2
	v_add_f32_e32 v160, v160, v161
	v_add_f32_e32 v156, v156, v157
	v_add_f32_e32 v166, v160, v156
	s_waitcnt vmcnt(4)
	v_pk_fma_f32 v[30:31], v[30:31], v[132:133], v[230:231]
	s_waitcnt vmcnt(4)
	v_pk_fma_f32 v[14:15], v[14:15], v[136:137], v[234:235]
	v_pk_fma_f32 v[12:13], v[12:13], v[134:135], v[232:233]
	v_mul_f32_e32 v161, v15, v15
	v_mul_f32_e32 v160, v13, v13
	v_pk_fma_f32 v[28:29], v[28:29], v[130:131], v[228:229]
	s_mov_b64 s[98:99], 0x30000
	v_lshl_add_u64 v[228:229], v[218:219], 0, s[98:99]
	global_load_dwordx4 v[232:235], v[228:229], off
	global_load_dwordx4 v[228:231], v[228:229], off offset:16
	v_fmac_f32_e32 v160, v12, v12
	v_fmac_f32_e32 v161, v14, v14
	v_mul_f32_e32 v156, v29, v29
	v_mul_f32_e32 v157, v31, v31
	v_add_f32_e32 v160, v160, v161
	v_fmac_f32_e32 v156, v28, v28
	v_fmac_f32_e32 v157, v30, v30
	v_add_f32_e32 v160, v166, v160
	v_add_f32_e32 v156, v156, v157
	v_add_f32_e32 v156, v160, v156
	ds_bpermute_b32 v157, v183, v156
	s_waitcnt lgkmcnt(0)
	v_add_f32_e32 v156, v156, v157
	ds_bpermute_b32 v157, v184, v156
	s_and_saveexec_b64 s[2:3], vcc
	s_cbranch_execz .LBB0_102
	s_lshl_b32 s11, s6, 2
	s_add_i32 s11, s11, 0
	v_lshl_add_u32 v158, v198, 4, s11
	s_waitcnt lgkmcnt(0)
	v_add_f32_e32 v156, v156, v157
	ds_write_b32 v158, v156 offset:256
.LBB0_102:
	s_or_b64 exec, exec, s[2:3]
	v_or_b32_e32 v156, 32, v152
	s_waitcnt lgkmcnt(0)
	v_ashrrev_i32_e32 v157, 31, v156
	v_lshlrev_b64 v[158:159], 12, v[156:157]
	v_lshl_add_u64 v[160:161], s[84:85], 0, v[158:159]
	v_lshl_add_u64 v[168:169], v[176:177], 2, v[160:161]
	s_waitcnt vmcnt(4)
	v_pk_fma_f32 v[34:35], v[34:35], v[144:145], v[238:239]
	s_waitcnt vmcnt(4)
	v_pk_fma_f32 v[38:39], v[38:39], v[140:141], v[242:243]
	v_pk_fma_f32 v[36:37], v[36:37], v[138:139], v[240:241]
	v_pk_fma_f32 v[32:33], v[32:33], v[142:143], v[236:237]
	s_mov_b64 s[98:99], 0x30000
	v_lshl_add_u64 v[236:237], v[218:219], 0, s[98:99]
	global_load_dwordx4 v[240:243], v[236:237], off offset:512
	global_load_dwordx4 v[236:239], v[236:237], off offset:528
	v_mul_f32_e32 v164, v37, v37
	v_mul_f32_e32 v165, v39, v39
	v_mul_f32_e32 v160, v33, v33
	v_mul_f32_e32 v161, v35, v35
	v_fmac_f32_e32 v164, v36, v36
	v_fmac_f32_e32 v165, v38, v38
	v_fmac_f32_e32 v160, v32, v32
	v_fmac_f32_e32 v161, v34, v34
	v_add_f32_e32 v164, v164, v165
	v_add_f32_e32 v160, v160, v161
	v_add_f32_e32 v170, v164, v160
	s_waitcnt vmcnt(4)
	v_pk_fma_f32 v[68:69], v[68:69], v[132:133], v[222:223]
	s_waitcnt vmcnt(4)
	v_pk_fma_f32 v[58:59], v[58:59], v[136:137], v[226:227]
	v_pk_fma_f32 v[56:57], v[56:57], v[134:135], v[224:225]
	v_mul_f32_e32 v165, v59, v59
	v_mul_f32_e32 v164, v57, v57
	v_pk_fma_f32 v[66:67], v[66:67], v[130:131], v[220:221]
	s_mov_b64 s[98:99], 0x80000
	v_lshl_add_u64 v[220:221], v[218:219], 0, s[98:99]
	global_load_dwordx4 v[224:227], v[220:221], off
	global_load_dwordx4 v[220:223], v[220:221], off offset:16
	v_fmac_f32_e32 v164, v56, v56
	v_fmac_f32_e32 v165, v58, v58
	v_mul_f32_e32 v160, v67, v67
	v_mul_f32_e32 v161, v69, v69
	v_add_f32_e32 v164, v164, v165
	v_fmac_f32_e32 v160, v66, v66
	v_fmac_f32_e32 v161, v68, v68
	v_add_f32_e32 v164, v170, v164
	v_add_f32_e32 v160, v160, v161
	v_add_f32_e32 v160, v164, v160
	ds_bpermute_b32 v161, v183, v160
	s_waitcnt lgkmcnt(0)
	v_add_f32_e32 v160, v160, v161
	ds_bpermute_b32 v161, v184, v160
	s_and_saveexec_b64 s[2:3], vcc
	s_cbranch_execz .LBB0_104
	s_lshl_b32 s11, s6, 2
	s_add_i32 s11, s11, 0
	v_lshl_add_u32 v162, v198, 4, s11
	s_waitcnt lgkmcnt(0)
	v_add_f32_e32 v160, v160, v161
	ds_write_b32 v162, v160 offset:512
.LBB0_104:
	s_or_b64 exec, exec, s[2:3]
	v_or_b32_e32 v160, 48, v152
	s_waitcnt lgkmcnt(0)
	v_ashrrev_i32_e32 v161, 31, v160
	v_lshlrev_b64 v[162:163], 12, v[160:161]
	v_lshl_add_u64 v[164:165], s[84:85], 0, v[162:163]
	v_lshl_add_u64 v[172:173], v[176:177], 2, v[164:165]
	s_waitcnt vmcnt(4)
	v_pk_fma_f32 v[76:77], v[76:77], v[144:145], v[230:231]
	s_waitcnt vmcnt(4)
	v_pk_fma_f32 v[80:81], v[80:81], v[140:141], v[234:235]
	v_pk_fma_f32 v[78:79], v[78:79], v[138:139], v[232:233]
	v_pk_fma_f32 v[74:75], v[74:75], v[142:143], v[228:229]
	s_mov_b64 s[98:99], 0x80000
	v_lshl_add_u64 v[228:229], v[218:219], 0, s[98:99]
	global_load_dwordx4 v[232:235], v[228:229], off offset:512
	global_load_dwordx4 v[228:231], v[228:229], off offset:528
	v_mul_f32_e32 v168, v79, v79
	v_mul_f32_e32 v169, v81, v81
	v_mul_f32_e32 v164, v75, v75
	v_mul_f32_e32 v165, v77, v77
	v_fmac_f32_e32 v168, v78, v78
	v_fmac_f32_e32 v169, v80, v80
	v_fmac_f32_e32 v164, v74, v74
	v_fmac_f32_e32 v165, v76, v76
	v_add_f32_e32 v168, v168, v169
	v_add_f32_e32 v164, v164, v165
	v_add_f32_e32 v174, v168, v164
	s_waitcnt vmcnt(4)
	v_pk_fma_f32 v[96:97], v[96:97], v[132:133], v[238:239]
	s_waitcnt vmcnt(4)
	v_pk_fma_f32 v[88:89], v[88:89], v[136:137], v[242:243]
	v_pk_fma_f32 v[86:87], v[86:87], v[134:135], v[240:241]
	v_mul_f32_e32 v169, v89, v89
	v_mul_f32_e32 v168, v87, v87
	v_pk_fma_f32 v[94:95], v[94:95], v[130:131], v[236:237]
	s_mov_b64 s[98:99], 0x90000
	v_lshl_add_u64 v[236:237], v[218:219], 0, s[98:99]
	global_load_dwordx4 v[240:243], v[236:237], off
	global_load_dwordx4 v[236:239], v[236:237], off offset:16
	v_fmac_f32_e32 v168, v86, v86
	v_fmac_f32_e32 v169, v88, v88
	v_mul_f32_e32 v164, v95, v95
	v_mul_f32_e32 v165, v97, v97
	v_add_f32_e32 v168, v168, v169
	v_fmac_f32_e32 v164, v94, v94
	v_fmac_f32_e32 v165, v96, v96
	v_add_f32_e32 v168, v174, v168
	v_add_f32_e32 v164, v164, v165
	v_add_f32_e32 v164, v168, v164
	ds_bpermute_b32 v165, v183, v164
	s_waitcnt lgkmcnt(0)
	v_add_f32_e32 v164, v164, v165
	ds_bpermute_b32 v165, v184, v164
	s_and_saveexec_b64 s[2:3], vcc
	s_cbranch_execz .LBB0_106
	s_lshl_b32 s11, s6, 2
	s_add_i32 s11, s11, 0
	v_lshl_add_u32 v166, v198, 4, s11
	s_waitcnt lgkmcnt(0)
	v_add_f32_e32 v164, v164, v165
	ds_write_b32 v166, v164 offset:768
.LBB0_106:
	s_or_b64 exec, exec, s[2:3]
	v_add_u32_e32 v164, 0x80, v152
	s_waitcnt lgkmcnt(0)
	v_ashrrev_i32_e32 v165, 31, v164
	v_lshlrev_b64 v[166:167], 12, v[164:165]
	v_lshl_add_u64 v[168:169], s[84:85], 0, v[166:167]
	v_lshl_add_u64 v[178:179], v[176:177], 2, v[168:169]
	s_waitcnt vmcnt(4)
	v_pk_fma_f32 v[104:105], v[104:105], v[144:145], v[222:223]
	s_waitcnt vmcnt(4)
	v_pk_fma_f32 v[108:109], v[108:109], v[140:141], v[226:227]
	v_pk_fma_f32 v[106:107], v[106:107], v[138:139], v[224:225]
	v_pk_fma_f32 v[102:103], v[102:103], v[142:143], v[220:221]
	s_mov_b64 s[98:99], 0x90000
	v_lshl_add_u64 v[220:221], v[218:219], 0, s[98:99]
	global_load_dwordx4 v[224:227], v[220:221], off offset:512
	global_load_dwordx4 v[220:223], v[220:221], off offset:528
	v_mul_f32_e32 v172, v107, v107
	v_mul_f32_e32 v173, v109, v109
	v_mul_f32_e32 v168, v103, v103
	v_mul_f32_e32 v169, v105, v105
	v_fmac_f32_e32 v172, v106, v106
	v_fmac_f32_e32 v173, v108, v108
	v_fmac_f32_e32 v168, v102, v102
	v_fmac_f32_e32 v169, v104, v104
	v_add_f32_e32 v172, v172, v173
	v_add_f32_e32 v168, v168, v169
	v_add_f32_e32 v180, v172, v168
	s_waitcnt vmcnt(4)
	v_pk_fma_f32 v[120:121], v[120:121], v[132:133], v[230:231]
	s_waitcnt vmcnt(4)
	v_pk_fma_f32 v[116:117], v[116:117], v[136:137], v[234:235]
	v_pk_fma_f32 v[114:115], v[114:115], v[134:135], v[232:233]
	v_mul_f32_e32 v173, v117, v117
	v_mul_f32_e32 v172, v115, v115
	v_pk_fma_f32 v[118:119], v[118:119], v[130:131], v[228:229]
	s_mov_b64 s[98:99], 0xa0000
	v_lshl_add_u64 v[228:229], v[218:219], 0, s[98:99]
	global_load_dwordx4 v[232:235], v[228:229], off
	global_load_dwordx4 v[228:231], v[228:229], off offset:16
	v_fmac_f32_e32 v172, v114, v114
	v_fmac_f32_e32 v173, v116, v116
	v_mul_f32_e32 v168, v119, v119
	v_mul_f32_e32 v169, v121, v121
	v_add_f32_e32 v172, v172, v173
	v_fmac_f32_e32 v168, v118, v118
	v_fmac_f32_e32 v169, v120, v120
	v_add_f32_e32 v172, v180, v172
	v_add_f32_e32 v168, v168, v169
	v_add_f32_e32 v168, v172, v168
	ds_bpermute_b32 v169, v183, v168
	s_waitcnt lgkmcnt(0)
	v_add_f32_e32 v168, v168, v169
	ds_bpermute_b32 v169, v184, v168
	s_and_saveexec_b64 s[2:3], vcc
	s_cbranch_execz .LBB0_108
	s_lshl_b32 s11, s6, 2
	s_add_i32 s11, s11, 0
	v_lshl_add_u32 v170, v198, 4, s11
	s_waitcnt lgkmcnt(0)
	v_add_f32_e32 v168, v168, v169
	ds_write_b32 v170, v168 offset:2048
.LBB0_108:
	s_or_b64 exec, exec, s[2:3]
	v_add_u32_e32 v168, 0x90, v152
	s_waitcnt lgkmcnt(0)
	v_ashrrev_i32_e32 v169, 31, v168
	v_lshlrev_b64 v[170:171], 12, v[168:169]
	v_lshl_add_u64 v[172:173], s[84:85], 0, v[170:171]
	v_lshl_add_u64 v[186:187], v[176:177], 2, v[172:173]
	s_waitcnt vmcnt(4)
	v_pk_fma_f32 v[124:125], v[124:125], v[144:145], v[238:239]
	s_waitcnt vmcnt(4)
	v_pk_fma_f32 v[128:129], v[128:129], v[140:141], v[242:243]
	v_pk_fma_f32 v[126:127], v[126:127], v[138:139], v[240:241]
	v_pk_fma_f32 v[122:123], v[122:123], v[142:143], v[236:237]
	s_mov_b64 s[98:99], 0xa0000
	v_lshl_add_u64 v[236:237], v[218:219], 0, s[98:99]
	global_load_dwordx4 v[240:243], v[236:237], off offset:512
	global_load_dwordx4 v[236:239], v[236:237], off offset:528
	v_mul_f32_e32 v178, v127, v127
	v_mul_f32_e32 v179, v129, v129
	v_mul_f32_e32 v172, v123, v123
	v_mul_f32_e32 v173, v125, v125
	v_fmac_f32_e32 v178, v126, v126
	v_fmac_f32_e32 v179, v128, v128
	v_fmac_f32_e32 v172, v122, v122
	v_fmac_f32_e32 v173, v124, v124
	v_add_f32_e32 v178, v178, v179
	v_add_f32_e32 v172, v172, v173
	v_add_f32_e32 v185, v178, v172
	s_waitcnt vmcnt(4)
	v_pk_fma_f32 v[100:101], v[100:101], v[132:133], v[222:223]
	s_waitcnt vmcnt(4)
	v_pk_fma_f32 v[112:113], v[112:113], v[136:137], v[226:227]
	v_pk_fma_f32 v[110:111], v[110:111], v[134:135], v[224:225]
	v_mul_f32_e32 v179, v113, v113
	v_mul_f32_e32 v178, v111, v111
	v_pk_fma_f32 v[98:99], v[98:99], v[130:131], v[220:221]
	s_mov_b64 s[98:99], 0xb0000
	v_lshl_add_u64 v[220:221], v[218:219], 0, s[98:99]
	global_load_dwordx4 v[224:227], v[220:221], off
	global_load_dwordx4 v[220:223], v[220:221], off offset:16
	v_fmac_f32_e32 v178, v110, v110
	v_fmac_f32_e32 v179, v112, v112
	v_mul_f32_e32 v172, v99, v99
	v_mul_f32_e32 v173, v101, v101
	v_add_f32_e32 v178, v178, v179
	v_fmac_f32_e32 v172, v98, v98
	v_fmac_f32_e32 v173, v100, v100
	v_add_f32_e32 v178, v185, v178
	v_add_f32_e32 v172, v172, v173
	v_add_f32_e32 v172, v178, v172
	ds_bpermute_b32 v173, v183, v172
	s_waitcnt lgkmcnt(0)
	v_add_f32_e32 v172, v172, v173
	ds_bpermute_b32 v173, v184, v172
	s_and_saveexec_b64 s[2:3], vcc
	s_cbranch_execz .LBB0_110
	s_lshl_b32 s11, s6, 2
	s_add_i32 s11, s11, 0
	v_lshl_add_u32 v174, v198, 4, s11
	s_waitcnt lgkmcnt(0)
	v_add_f32_e32 v172, v172, v173
	ds_write_b32 v174, v172 offset:2304
.LBB0_110:
	s_or_b64 exec, exec, s[2:3]
	v_add_u32_e32 v172, 0xa0, v152
	s_waitcnt lgkmcnt(0)
	v_ashrrev_i32_e32 v173, 31, v172
	v_lshlrev_b64 v[174:175], 12, v[172:173]
	v_lshl_add_u64 v[178:179], s[84:85], 0, v[174:175]
	v_lshl_add_u64 v[186:187], v[176:177], 2, v[178:179]
	s_waitcnt vmcnt(4)
	v_pk_fma_f32 v[84:85], v[84:85], v[144:145], v[230:231]
	s_waitcnt vmcnt(4)
	v_pk_fma_f32 v[92:93], v[92:93], v[140:141], v[234:235]
	v_pk_fma_f32 v[90:91], v[90:91], v[138:139], v[232:233]
	v_pk_fma_f32 v[82:83], v[82:83], v[142:143], v[228:229]
	s_mov_b64 s[98:99], 0xb0000
	v_lshl_add_u64 v[228:229], v[218:219], 0, s[98:99]
	global_load_dwordx4 v[232:235], v[228:229], off offset:512
	global_load_dwordx4 v[228:231], v[228:229], off offset:528
	v_mul_f32_e32 v185, v91, v91
	v_mul_f32_e32 v190, v93, v93
	v_mul_f32_e32 v178, v83, v83
	v_mul_f32_e32 v179, v85, v85
	v_fmac_f32_e32 v185, v90, v90
	v_fmac_f32_e32 v190, v92, v92
	v_fmac_f32_e32 v178, v82, v82
	v_fmac_f32_e32 v179, v84, v84
	v_add_f32_e32 v185, v185, v190
	v_add_f32_e32 v178, v178, v179
	v_add_f32_e32 v185, v185, v178
	s_waitcnt vmcnt(4)
	v_pk_fma_f32 v[62:63], v[62:63], v[132:133], v[238:239]
	s_waitcnt vmcnt(4)
	v_pk_fma_f32 v[72:73], v[72:73], v[136:137], v[242:243]
	v_pk_fma_f32 v[70:71], v[70:71], v[134:135], v[240:241]
	v_mul_f32_e32 v187, v73, v73
	v_mul_f32_e32 v186, v71, v71
	v_pk_fma_f32 v[60:61], v[60:61], v[130:131], v[236:237]
	v_fmac_f32_e32 v186, v70, v70
	v_fmac_f32_e32 v187, v72, v72
	v_mul_f32_e32 v178, v61, v61
	v_mul_f32_e32 v179, v63, v63
	v_add_f32_e32 v186, v186, v187
	v_fmac_f32_e32 v178, v60, v60
	v_fmac_f32_e32 v179, v62, v62
	v_add_f32_e32 v185, v185, v186
	v_add_f32_e32 v178, v178, v179
	v_add_f32_e32 v178, v185, v178
	ds_bpermute_b32 v179, v183, v178
	s_waitcnt lgkmcnt(0)
	v_add_f32_e32 v178, v178, v179
	ds_bpermute_b32 v179, v184, v178
	s_and_saveexec_b64 s[2:3], vcc
	s_cbranch_execz .LBB0_112
	s_lshl_b32 s11, s6, 2
	s_add_i32 s11, s11, 0
	v_lshl_add_u32 v180, v198, 4, s11
	s_waitcnt lgkmcnt(0)
	v_add_f32_e32 v178, v178, v179
	ds_write_b32 v180, v178 offset:2560
.LBB0_112:
	s_or_b64 exec, exec, s[2:3]
	v_add_u32_e32 v178, 0xb0, v152
	s_waitcnt lgkmcnt(0)
	v_ashrrev_i32_e32 v179, 31, v178
	v_lshlrev_b64 v[180:181], 12, v[178:179]
	v_lshl_add_u64 v[186:187], s[84:85], 0, v[180:181]
	v_lshl_add_u64 v[176:177], v[176:177], 2, v[186:187]
	s_waitcnt vmcnt(2)
	v_pk_fma_f32 v[42:43], v[42:43], v[144:145], v[222:223]
	s_waitcnt vmcnt(2)
	v_pk_fma_f32 v[46:47], v[46:47], v[140:141], v[226:227]
	v_pk_fma_f32 v[44:45], v[44:45], v[138:139], v[224:225]
	v_mul_f32_e32 v139, v47, v47
	v_mul_f32_e32 v138, v45, v45
	v_fmac_f32_e32 v138, v44, v44
	v_fmac_f32_e32 v139, v46, v46
	v_pk_fma_f32 v[40:41], v[40:41], v[142:143], v[220:221]
	v_add_f32_e32 v138, v138, v139
	v_mul_f32_e32 v139, v41, v41
	v_mul_f32_e32 v140, v43, v43
	v_fmac_f32_e32 v139, v40, v40
	v_fmac_f32_e32 v140, v42, v42
	v_add_f32_e32 v139, v139, v140
	v_add_f32_e32 v185, v138, v139
	s_waitcnt vmcnt(0)
	v_pk_fma_f32 v[10:11], v[10:11], v[132:133], v[230:231]
	s_waitcnt vmcnt(0)
	v_pk_fma_f32 v[18:19], v[18:19], v[136:137], v[234:235]
	v_pk_fma_f32 v[16:17], v[16:17], v[134:135], v[232:233]
	v_mul_f32_e32 v135, v19, v19
	v_mul_f32_e32 v134, v17, v17
	v_pk_fma_f32 v[8:9], v[8:9], v[130:131], v[228:229]
	v_fmac_f32_e32 v134, v16, v16
	v_fmac_f32_e32 v135, v18, v18
	v_mul_f32_e32 v130, v9, v9
	v_mul_f32_e32 v131, v11, v11
	v_add_f32_e32 v134, v134, v135
	v_fmac_f32_e32 v130, v8, v8
	v_fmac_f32_e32 v131, v10, v10
	v_add_f32_e32 v134, v185, v134
	v_add_f32_e32 v130, v130, v131
	v_add_f32_e32 v130, v134, v130
	ds_bpermute_b32 v131, v183, v130
	s_waitcnt lgkmcnt(0)
	v_add_f32_e32 v130, v130, v131
	ds_bpermute_b32 v131, v184, v130
	s_and_saveexec_b64 s[2:3], vcc
	s_cbranch_execz .LBB0_114
	s_lshl_b32 s6, s6, 2
	s_add_i32 s6, s6, 0
	s_waitcnt lgkmcnt(0)
	v_add_f32_e32 v130, v130, v131
	v_lshl_add_u32 v131, v198, 4, s6
	ds_write_b32 v131, v130 offset:2816

.LBB0_698:
	s_ashr_i32 s2, s40, 4
	s_mul_hi_i32 s3, s2, 0x1800
	s_mulk_i32 s2, 0x1800
	s_lshl_b32 s11, s10, 5
	s_lshl_b32 s17, s40, 8
	s_lshl_b32 s46, s80, 8
	s_lshl_b64 s[86:87], s[2:3], 2
	v_readlane_b32 s2, v254, 41
	v_mov_b32_e32 v182, v203
	v_readlane_b32 s3, v254, 42
	s_add_u32 s2, s2, s86
	s_waitcnt vmcnt(0)
	s_barrier
	s_waitcnt vmcnt(0)
	s_barrier
	s_addc_u32 s3, s3, s87
	v_and_b32_e32 v150, 15, v182
	v_bfe_u32 v151, v182, 4, 2
	s_add_i32 s41, s17, s22
	v_or_b32_e32 v152, s41, v150
	v_lshlrev_b32_e32 v64, 3, v151
	s_or_b32 s41, s46, s11
	v_or_b32_e32 v164, s41, v64
	v_ashrrev_i32_e32 v165, 31, v164
	v_ashrrev_i32_e32 v153, 31, v152
	v_lshlrev_b64 v[160:161], 2, v[164:165]
	v_lshlrev_b64 v[130:131], 12, v[152:153]
	v_lshl_add_u64 v[132:133], s[2:3], 0, v[160:161]
	s_movk_i32 s2, 0x5000
	v_add_co_u32_e32 v134, vcc, s2, v132
	v_lshl_add_u64 v[130:131], s[0:1], 0, v[130:131]
	s_nop 0
	v_addc_co_u32_e32 v135, vcc, 0, v133, vcc
	v_lshl_add_u64 v[148:149], v[130:131], 0, v[160:161]
	global_load_dwordx4 v[138:141], v[134:135], off
	v_mov_b32_e32 v218, v148
	v_mov_b32_e32 v219, v149
	global_load_dwordx4 v[154:157], v[148:149], off offset:16
	global_load_dwordx4 v[166:169], v[148:149], off
	s_mov_b64 s[2:3], 0x5000
	v_lshl_add_u64 v[130:131], v[132:133], 0, s[2:3]
	global_load_dwordx4 v[142:145], v[130:131], off offset:16
	global_load_dwordx4 v[134:137], v[130:131], off offset:512
	global_load_dwordx4 v[170:173], v[148:149], off offset:512
	global_load_dwordx4 v[174:177], v[148:149], off offset:528
	s_nop 0
	global_load_dwordx4 v[130:133], v[130:131], off offset:528
	s_mov_b64 s[98:99], 0x10000
	v_lshl_add_u64 v[220:221], v[218:219], 0, s[98:99]
	global_load_dwordx4 v[224:227], v[220:221], off
	global_load_dwordx4 v[220:223], v[220:221], off offset:16
	s_mov_b64 s[98:99], 0x10000
	v_lshl_add_u64 v[228:229], v[218:219], 0, s[98:99]
	global_load_dwordx4 v[232:235], v[228:229], off offset:512
	global_load_dwordx4 v[228:231], v[228:229], off offset:528
	s_mov_b64 s[98:99], 0x20000
	v_lshl_add_u64 v[236:237], v[218:219], 0, s[98:99]
	global_load_dwordx4 v[240:243], v[236:237], off
	global_load_dwordx4 v[236:239], v[236:237], off offset:16
	v_and_b32_e32 v147, 64, v203
	v_xor_b32_e32 v146, 16, v203
	v_add_u32_e32 v147, 64, v147
	v_cmp_lt_i32_e32 vcc, v146, v147
	v_or_b32_e32 v196, s22, v150
	s_waitcnt vmcnt(10)
	v_pk_fma_f32 v[46:47], v[46:47], v[144:145], v[156:157]
	v_cndmask_b32_e32 v146, v203, v146, vcc
	v_pk_fma_f32 v[50:51], v[50:51], v[140:141], v[168:169]
	v_pk_fma_f32 v[48:49], v[48:49], v[138:139], v[166:167]
	v_pk_fma_f32 v[44:45], v[44:45], v[142:143], v[154:155]
	v_lshlrev_b32_e32 v183, 2, v146
	s_waitcnt vmcnt(8)
	v_pk_fma_f32 v[18:19], v[18:19], v[136:137], v[172:173]
	v_pk_fma_f32 v[16:17], v[16:17], v[134:135], v[170:171]
	v_mul_f32_e32 v146, v49, v49
	v_mul_f32_e32 v154, v51, v51
	v_mul_f32_e32 v155, v45, v45
	v_mul_f32_e32 v156, v47, v47
	s_waitcnt vmcnt(6)
	v_pk_fma_f32 v[10:11], v[10:11], v[132:133], v[176:177]
	v_pk_fma_f32 v[8:9], v[8:9], v[130:131], v[174:175]
	v_mul_f32_e32 v157, v17, v17
	v_mul_f32_e32 v158, v19, v19
	v_fmac_f32_e32 v146, v48, v48
	v_fmac_f32_e32 v154, v50, v50
	v_fmac_f32_e32 v155, v44, v44
	v_fmac_f32_e32 v156, v46, v46
	v_mul_f32_e32 v159, v9, v9
	v_mul_f32_e32 v162, v11, v11
	v_fmac_f32_e32 v157, v16, v16
	v_fmac_f32_e32 v158, v18, v18
	v_add_f32_e32 v146, v146, v154
	v_add_f32_e32 v154, v155, v156
	v_fmac_f32_e32 v159, v8, v8
	v_fmac_f32_e32 v162, v10, v10
	v_add_f32_e32 v155, v157, v158
	v_add_f32_e32 v146, v146, v154
	v_add_f32_e32 v146, v146, v155
	v_add_f32_e32 v154, v159, v162
	v_add_f32_e32 v146, v146, v154
	ds_bpermute_b32 v154, v183, v146
	v_xor_b32_e32 v155, 32, v203
	v_cmp_lt_i32_e32 vcc, v155, v147
	s_waitcnt lgkmcnt(0)
	v_add_f32_e32 v146, v146, v154
	v_cndmask_b32_e32 v147, v203, v155, vcc
	v_lshlrev_b32_e32 v184, 2, v147
	ds_bpermute_b32 v147, v184, v146
	v_cmp_eq_u32_e32 vcc, 0, v151
	s_and_saveexec_b64 s[2:3], vcc
	v_readlane_b32 s90, v253, 56
	v_readlane_b32 s91, v253, 57
	s_mov_b32 s88, s62
	s_cbranch_execz .LBB0_700
	s_lshl_b32 s22, s10, 2
	s_add_i32 s22, s22, 0
	v_lshl_add_u32 v150, v196, 4, s22
	s_waitcnt lgkmcnt(0)
	v_add_f32_e32 v146, v146, v147
	ds_write_b32 v150, v146
.LBB0_700:
	s_or_b64 exec, exec, s[2:3]
	v_or_b32_e32 v150, 16, v152
	v_ashrrev_i32_e32 v151, 31, v150
	s_waitcnt lgkmcnt(0)
	v_lshlrev_b64 v[146:147], 12, v[150:151]
	v_lshl_add_u64 v[146:147], s[0:1], 0, v[146:147]
	v_lshl_add_u64 v[146:147], v[164:165], 2, v[146:147]
	s_waitcnt vmcnt(4)
	v_pk_fma_f32 v[2:3], v[2:3], v[144:145], v[222:223]
	s_waitcnt vmcnt(4)
	v_pk_fma_f32 v[6:7], v[6:7], v[140:141], v[226:227]
	v_pk_fma_f32 v[4:5], v[4:5], v[138:139], v[224:225]
	v_pk_fma_f32 v[0:1], v[0:1], v[142:143], v[220:221]
	s_mov_b64 s[98:99], 0x20000
	v_lshl_add_u64 v[220:221], v[218:219], 0, s[98:99]
	global_load_dwordx4 v[224:227], v[220:221], off offset:512
	global_load_dwordx4 v[220:223], v[220:221], off offset:528
	v_mul_f32_e32 v158, v5, v5
	v_mul_f32_e32 v159, v7, v7
	v_mul_f32_e32 v154, v1, v1
	v_mul_f32_e32 v155, v3, v3
	v_fmac_f32_e32 v158, v4, v4
	v_fmac_f32_e32 v159, v6, v6
	v_fmac_f32_e32 v154, v0, v0
	v_fmac_f32_e32 v155, v2, v2
	v_add_f32_e32 v158, v158, v159
	v_add_f32_e32 v154, v154, v155
	v_add_f32_e32 v158, v158, v154
	s_waitcnt vmcnt(4)
	v_pk_fma_f32 v[30:31], v[30:31], v[132:133], v[230:231]
	s_waitcnt vmcnt(4)
	v_pk_fma_f32 v[26:27], v[26:27], v[136:137], v[234:235]
	v_pk_fma_f32 v[24:25], v[24:25], v[134:135], v[232:233]
	v_mul_f32_e32 v162, v27, v27
	v_mul_f32_e32 v159, v25, v25
	v_pk_fma_f32 v[28:29], v[28:29], v[130:131], v[228:229]
	s_mov_b64 s[98:99], 0x30000
	v_lshl_add_u64 v[228:229], v[218:219], 0, s[98:99]
	global_load_dwordx4 v[232:235], v[228:229], off
	global_load_dwordx4 v[228:231], v[228:229], off offset:16
	v_fmac_f32_e32 v159, v24, v24
	v_fmac_f32_e32 v162, v26, v26
	v_mul_f32_e32 v154, v29, v29
	v_mul_f32_e32 v155, v31, v31
	v_add_f32_e32 v159, v159, v162
	v_fmac_f32_e32 v154, v28, v28
	v_fmac_f32_e32 v155, v30, v30
	v_add_f32_e32 v158, v158, v159
	v_add_f32_e32 v154, v154, v155
	v_add_f32_e32 v154, v158, v154
	ds_bpermute_b32 v155, v183, v154
	s_waitcnt lgkmcnt(0)
	v_add_f32_e32 v154, v154, v155
	ds_bpermute_b32 v155, v184, v154
	s_and_saveexec_b64 s[2:3], vcc
	s_cbranch_execz .LBB0_702
	s_lshl_b32 s22, s10, 2
	s_add_i32 s22, s22, 0
	v_lshl_add_u32 v156, v196, 4, s22
	s_waitcnt lgkmcnt(0)
	v_add_f32_e32 v154, v154, v155
	ds_write_b32 v156, v154 offset:256
.LBB0_702:
	s_or_b64 exec, exec, s[2:3]
	v_or_b32_e32 v156, 32, v152
	v_ashrrev_i32_e32 v157, 31, v156
	s_waitcnt lgkmcnt(0)
	v_lshlrev_b64 v[154:155], 12, v[156:157]
	v_lshl_add_u64 v[154:155], s[0:1], 0, v[154:155]
	v_lshl_add_u64 v[154:155], v[164:165], 2, v[154:155]
	s_waitcnt vmcnt(4)
	v_pk_fma_f32 v[34:35], v[34:35], v[144:145], v[238:239]
	s_waitcnt vmcnt(4)
	v_pk_fma_f32 v[38:39], v[38:39], v[140:141], v[242:243]
	v_pk_fma_f32 v[36:37], v[36:37], v[138:139], v[240:241]
	v_pk_fma_f32 v[32:33], v[32:33], v[142:143], v[236:237]
	s_mov_b64 s[98:99], 0x30000
	v_lshl_add_u64 v[236:237], v[218:219], 0, s[98:99]
	global_load_dwordx4 v[240:243], v[236:237], off offset:512
	global_load_dwordx4 v[236:239], v[236:237], off offset:528
	v_mul_f32_e32 v158, v37, v37
	v_mul_f32_e32 v159, v39, v39
	v_fmac_f32_e32 v158, v36, v36
	v_fmac_f32_e32 v159, v38, v38
	v_add_f32_e32 v158, v158, v159
	v_mul_f32_e32 v159, v33, v33
	v_mul_f32_e32 v162, v35, v35
	v_fmac_f32_e32 v159, v32, v32
	v_fmac_f32_e32 v162, v34, v34
	v_add_f32_e32 v159, v159, v162
	v_add_f32_e32 v158, v158, v159
	s_waitcnt vmcnt(4)
	v_pk_fma_f32 v[68:69], v[68:69], v[132:133], v[222:223]
	s_waitcnt vmcnt(4)
	v_pk_fma_f32 v[58:59], v[58:59], v[136:137], v[226:227]
	v_pk_fma_f32 v[56:57], v[56:57], v[134:135], v[224:225]
	v_mul_f32_e32 v162, v59, v59
	v_mul_f32_e32 v159, v57, v57
	v_fmac_f32_e32 v159, v56, v56
	v_fmac_f32_e32 v162, v58, v58
	v_add_f32_e32 v159, v159, v162
	v_pk_fma_f32 v[66:67], v[66:67], v[130:131], v[220:221]
	s_mov_b64 s[98:99], 0x80000
	v_lshl_add_u64 v[220:221], v[218:219], 0, s[98:99]
	global_load_dwordx4 v[224:227], v[220:221], off
	global_load_dwordx4 v[220:223], v[220:221], off offset:16
	v_add_f32_e32 v158, v158, v159
	v_mul_f32_e32 v159, v67, v67
	v_mul_f32_e32 v162, v69, v69
	v_fmac_f32_e32 v159, v66, v66
	v_fmac_f32_e32 v162, v68, v68
	v_add_f32_e32 v159, v159, v162
	v_add_f32_e32 v158, v158, v159
	ds_bpermute_b32 v159, v183, v158
	s_waitcnt lgkmcnt(0)
	v_add_f32_e32 v158, v158, v159
	ds_bpermute_b32 v159, v184, v158
	s_and_saveexec_b64 s[2:3], vcc
	s_cbranch_execz .LBB0_704
	s_lshl_b32 s22, s10, 2
	s_add_i32 s22, s22, 0
	v_lshl_add_u32 v162, v196, 4, s22
	s_waitcnt lgkmcnt(0)
	v_add_f32_e32 v158, v158, v159
	ds_write_b32 v162, v158 offset:512
.LBB0_704:
	s_or_b64 exec, exec, s[2:3]
	v_or_b32_e32 v162, 48, v152
	v_ashrrev_i32_e32 v163, 31, v162
	s_waitcnt lgkmcnt(0)
	v_lshlrev_b64 v[158:159], 12, v[162:163]
	v_lshl_add_u64 v[158:159], s[0:1], 0, v[158:159]
	v_lshl_add_u64 v[158:159], v[164:165], 2, v[158:159]
	s_waitcnt vmcnt(4)
	v_pk_fma_f32 v[76:77], v[76:77], v[144:145], v[230:231]
	s_waitcnt vmcnt(4)
	v_pk_fma_f32 v[80:81], v[80:81], v[140:141], v[234:235]
	v_pk_fma_f32 v[78:79], v[78:79], v[138:139], v[232:233]
	v_pk_fma_f32 v[74:75], v[74:75], v[142:143], v[228:229]
	s_mov_b64 s[98:99], 0x80000
	v_lshl_add_u64 v[228:229], v[218:219], 0, s[98:99]
	global_load_dwordx4 v[232:235], v[228:229], off offset:512
	global_load_dwordx4 v[228:231], v[228:229], off offset:528
	v_mul_f32_e32 v170, v79, v79
	v_mul_f32_e32 v171, v81, v81
	v_mul_f32_e32 v166, v75, v75
	v_mul_f32_e32 v167, v77, v77
	v_fmac_f32_e32 v170, v78, v78
	v_fmac_f32_e32 v171, v80, v80
	v_fmac_f32_e32 v166, v74, v74
	v_fmac_f32_e32 v167, v76, v76
	v_add_f32_e32 v170, v170, v171
	v_add_f32_e32 v166, v166, v167
	v_add_f32_e32 v174, v170, v166
	s_waitcnt vmcnt(4)
	v_pk_fma_f32 v[96:97], v[96:97], v[132:133], v[238:239]
	s_waitcnt vmcnt(4)
	v_pk_fma_f32 v[88:89], v[88:89], v[136:137], v[242:243]
	v_pk_fma_f32 v[86:87], v[86:87], v[134:135], v[240:241]
	v_mul_f32_e32 v171, v89, v89
	v_mul_f32_e32 v170, v87, v87
	v_pk_fma_f32 v[94:95], v[94:95], v[130:131], v[236:237]
	s_mov_b64 s[98:99], 0x90000
	v_lshl_add_u64 v[236:237], v[218:219], 0, s[98:99]
	global_load_dwordx4 v[240:243], v[236:237], off
	global_load_dwordx4 v[236:239], v[236:237], off offset:16
	v_fmac_f32_e32 v170, v86, v86
	v_fmac_f32_e32 v171, v88, v88
	v_mul_f32_e32 v166, v95, v95
	v_mul_f32_e32 v167, v97, v97
	v_add_f32_e32 v170, v170, v171
	v_fmac_f32_e32 v166, v94, v94
	v_fmac_f32_e32 v167, v96, v96
	v_add_f32_e32 v170, v174, v170
	v_add_f32_e32 v166, v166, v167
	v_add_f32_e32 v166, v170, v166
	ds_bpermute_b32 v167, v183, v166
	s_waitcnt lgkmcnt(0)
	v_add_f32_e32 v166, v166, v167
	ds_bpermute_b32 v167, v184, v166
	s_and_saveexec_b64 s[2:3], vcc
	s_cbranch_execz .LBB0_706
	s_lshl_b32 s22, s10, 2
	s_add_i32 s22, s22, 0
	v_lshl_add_u32 v168, v196, 4, s22
	s_waitcnt lgkmcnt(0)
	v_add_f32_e32 v166, v166, v167
	ds_write_b32 v168, v166 offset:768
.LBB0_706:
	s_or_b64 exec, exec, s[2:3]
	v_add_u32_e32 v168, 0x80, v152
	v_ashrrev_i32_e32 v169, 31, v168
	s_waitcnt lgkmcnt(0)
	v_lshlrev_b64 v[166:167], 12, v[168:169]
	v_lshl_add_u64 v[166:167], s[0:1], 0, v[166:167]
	v_lshl_add_u64 v[166:167], v[164:165], 2, v[166:167]
	s_waitcnt vmcnt(4)
	v_pk_fma_f32 v[104:105], v[104:105], v[144:145], v[222:223]
	s_waitcnt vmcnt(4)
	v_pk_fma_f32 v[108:109], v[108:109], v[140:141], v[226:227]
	v_pk_fma_f32 v[106:107], v[106:107], v[138:139], v[224:225]
	v_pk_fma_f32 v[102:103], v[102:103], v[142:143], v[220:221]
	s_mov_b64 s[98:99], 0x90000
	v_lshl_add_u64 v[220:221], v[218:219], 0, s[98:99]
	global_load_dwordx4 v[224:227], v[220:221], off offset:512
	global_load_dwordx4 v[220:223], v[220:221], off offset:528
	v_mul_f32_e32 v174, v107, v107
	v_mul_f32_e32 v175, v109, v109
	v_mul_f32_e32 v170, v103, v103
	v_mul_f32_e32 v171, v105, v105
	v_fmac_f32_e32 v174, v106, v106
	v_fmac_f32_e32 v175, v108, v108
	v_fmac_f32_e32 v170, v102, v102
	v_fmac_f32_e32 v171, v104, v104
	v_add_f32_e32 v174, v174, v175
	v_add_f32_e32 v170, v170, v171
	v_add_f32_e32 v178, v174, v170
	s_waitcnt vmcnt(4)
	v_pk_fma_f32 v[120:121], v[120:121], v[132:133], v[230:231]
	s_waitcnt vmcnt(4)
	v_pk_fma_f32 v[116:117], v[116:117], v[136:137], v[234:235]
	v_pk_fma_f32 v[114:115], v[114:115], v[134:135], v[232:233]
	v_mul_f32_e32 v175, v117, v117
	v_mul_f32_e32 v174, v115, v115
	v_pk_fma_f32 v[118:119], v[118:119], v[130:131], v[228:229]
	s_mov_b64 s[98:99], 0xa0000
	v_lshl_add_u64 v[228:229], v[218:219], 0, s[98:99]
	global_load_dwordx4 v[232:235], v[228:229], off
	global_load_dwordx4 v[228:231], v[228:229], off offset:16
	v_fmac_f32_e32 v174, v114, v114
	v_fmac_f32_e32 v175, v116, v116
	v_mul_f32_e32 v170, v119, v119
	v_mul_f32_e32 v171, v121, v121
	v_add_f32_e32 v174, v174, v175
	v_fmac_f32_e32 v170, v118, v118
	v_fmac_f32_e32 v171, v120, v120
	v_add_f32_e32 v174, v178, v174
	v_add_f32_e32 v170, v170, v171
	v_add_f32_e32 v170, v174, v170
	ds_bpermute_b32 v171, v183, v170
	s_waitcnt lgkmcnt(0)
	v_add_f32_e32 v170, v170, v171
	ds_bpermute_b32 v171, v184, v170
	s_and_saveexec_b64 s[2:3], vcc
	s_cbranch_execz .LBB0_708
	s_lshl_b32 s22, s10, 2
	s_add_i32 s22, s22, 0
	v_lshl_add_u32 v172, v196, 4, s22
	s_waitcnt lgkmcnt(0)
	v_add_f32_e32 v170, v170, v171
	ds_write_b32 v172, v170 offset:2048
.LBB0_708:
	s_or_b64 exec, exec, s[2:3]
	v_add_u32_e32 v172, 0x90, v152
	v_ashrrev_i32_e32 v173, 31, v172
	s_waitcnt lgkmcnt(0)
	v_lshlrev_b64 v[170:171], 12, v[172:173]
	v_lshl_add_u64 v[170:171], s[0:1], 0, v[170:171]
	v_lshl_add_u64 v[170:171], v[164:165], 2, v[170:171]
	s_waitcnt vmcnt(4)
	v_pk_fma_f32 v[124:125], v[124:125], v[144:145], v[238:239]
	s_waitcnt vmcnt(4)
	v_pk_fma_f32 v[128:129], v[128:129], v[140:141], v[242:243]
	v_pk_fma_f32 v[126:127], v[126:127], v[138:139], v[240:241]
	v_pk_fma_f32 v[122:123], v[122:123], v[142:143], v[236:237]
	s_mov_b64 s[98:99], 0xa0000
	v_lshl_add_u64 v[236:237], v[218:219], 0, s[98:99]
	global_load_dwordx4 v[240:243], v[236:237], off offset:512
	global_load_dwordx4 v[236:239], v[236:237], off offset:528
	v_mul_f32_e32 v178, v127, v127
	v_mul_f32_e32 v179, v129, v129
	v_mul_f32_e32 v174, v123, v123
	v_mul_f32_e32 v175, v125, v125
	v_fmac_f32_e32 v178, v126, v126
	v_fmac_f32_e32 v179, v128, v128
	v_fmac_f32_e32 v174, v122, v122
	v_fmac_f32_e32 v175, v124, v124
	v_add_f32_e32 v178, v178, v179
	v_add_f32_e32 v174, v174, v175
	v_add_f32_e32 v185, v178, v174
	s_waitcnt vmcnt(4)
	v_pk_fma_f32 v[100:101], v[100:101], v[132:133], v[222:223]
	s_waitcnt vmcnt(4)
	v_pk_fma_f32 v[112:113], v[112:113], v[136:137], v[226:227]
	v_pk_fma_f32 v[110:111], v[110:111], v[134:135], v[224:225]
	v_mul_f32_e32 v179, v113, v113
	v_mul_f32_e32 v178, v111, v111
	v_pk_fma_f32 v[98:99], v[98:99], v[130:131], v[220:221]
	s_mov_b64 s[98:99], 0xb0000
	v_lshl_add_u64 v[220:221], v[218:219], 0, s[98:99]
	global_load_dwordx4 v[224:227], v[220:221], off
	global_load_dwordx4 v[220:223], v[220:221], off offset:16
	v_fmac_f32_e32 v178, v110, v110
	v_fmac_f32_e32 v179, v112, v112
	v_mul_f32_e32 v174, v99, v99
	v_mul_f32_e32 v175, v101, v101
	v_add_f32_e32 v178, v178, v179
	v_fmac_f32_e32 v174, v98, v98
	v_fmac_f32_e32 v175, v100, v100
	v_add_f32_e32 v178, v185, v178
	v_add_f32_e32 v174, v174, v175
	v_add_f32_e32 v174, v178, v174
	ds_bpermute_b32 v175, v183, v174
	s_waitcnt lgkmcnt(0)
	v_add_f32_e32 v174, v174, v175
	ds_bpermute_b32 v175, v184, v174
	s_and_saveexec_b64 s[2:3], vcc
	s_cbranch_execz .LBB0_710
	s_lshl_b32 s22, s10, 2
	s_add_i32 s22, s22, 0
	v_lshl_add_u32 v176, v196, 4, s22
	s_waitcnt lgkmcnt(0)
	v_add_f32_e32 v174, v174, v175
	ds_write_b32 v176, v174 offset:2304
.LBB0_710:
	s_or_b64 exec, exec, s[2:3]
	v_add_u32_e32 v176, 0xa0, v152
	v_ashrrev_i32_e32 v177, 31, v176
	s_waitcnt lgkmcnt(0)
	v_lshlrev_b64 v[174:175], 12, v[176:177]
	v_lshl_add_u64 v[174:175], s[0:1], 0, v[174:175]
	v_lshl_add_u64 v[174:175], v[164:165], 2, v[174:175]
	s_waitcnt vmcnt(4)
	v_pk_fma_f32 v[84:85], v[84:85], v[144:145], v[230:231]
	s_waitcnt vmcnt(4)
	v_pk_fma_f32 v[92:93], v[92:93], v[140:141], v[234:235]
	v_pk_fma_f32 v[90:91], v[90:91], v[138:139], v[232:233]
	v_pk_fma_f32 v[82:83], v[82:83], v[142:143], v[228:229]
	s_mov_b64 s[98:99], 0xb0000
	v_lshl_add_u64 v[228:229], v[218:219], 0, s[98:99]
	global_load_dwordx4 v[232:235], v[228:229], off offset:512
	global_load_dwordx4 v[228:231], v[228:229], off offset:528
	v_mul_f32_e32 v185, v91, v91
	v_mul_f32_e32 v186, v93, v93
	v_mul_f32_e32 v178, v83, v83
	v_mul_f32_e32 v179, v85, v85
	v_fmac_f32_e32 v185, v90, v90
	v_fmac_f32_e32 v186, v92, v92
	v_fmac_f32_e32 v178, v82, v82
	v_fmac_f32_e32 v179, v84, v84
	v_add_f32_e32 v185, v185, v186
	v_add_f32_e32 v178, v178, v179
	v_add_f32_e32 v185, v185, v178
	s_waitcnt vmcnt(4)
	v_pk_fma_f32 v[62:63], v[62:63], v[132:133], v[238:239]
	s_waitcnt vmcnt(4)
	v_pk_fma_f32 v[72:73], v[72:73], v[136:137], v[242:243]
	v_pk_fma_f32 v[70:71], v[70:71], v[134:135], v[240:241]
	v_mul_f32_e32 v187, v73, v73
	v_mul_f32_e32 v186, v71, v71
	v_pk_fma_f32 v[60:61], v[60:61], v[130:131], v[236:237]
	v_fmac_f32_e32 v186, v70, v70
	v_fmac_f32_e32 v187, v72, v72
	v_mul_f32_e32 v178, v61, v61
	v_mul_f32_e32 v179, v63, v63
	v_add_f32_e32 v186, v186, v187
	v_fmac_f32_e32 v178, v60, v60
	v_fmac_f32_e32 v179, v62, v62
	v_add_f32_e32 v185, v185, v186
	v_add_f32_e32 v178, v178, v179
	v_add_f32_e32 v178, v185, v178
	ds_bpermute_b32 v179, v183, v178
	s_waitcnt lgkmcnt(0)
	v_add_f32_e32 v178, v178, v179
	ds_bpermute_b32 v179, v184, v178
	s_and_saveexec_b64 s[2:3], vcc
	s_cbranch_execz .LBB0_712
	s_lshl_b32 s22, s10, 2
	s_add_i32 s22, s22, 0
	v_lshl_add_u32 v180, v196, 4, s22
	s_waitcnt lgkmcnt(0)
	v_add_f32_e32 v178, v178, v179
	ds_write_b32 v180, v178 offset:2560
.LBB0_712:
	s_or_b64 exec, exec, s[2:3]
	v_add_u32_e32 v180, 0xb0, v152
	v_ashrrev_i32_e32 v181, 31, v180
	s_waitcnt lgkmcnt(0)
	v_lshlrev_b64 v[178:179], 12, v[180:181]
	v_lshl_add_u64 v[178:179], s[0:1], 0, v[178:179]
	v_lshl_add_u64 v[178:179], v[164:165], 2, v[178:179]
	s_waitcnt vmcnt(2)
	v_pk_fma_f32 v[42:43], v[42:43], v[144:145], v[222:223]
	s_waitcnt vmcnt(2)
	v_pk_fma_f32 v[54:55], v[54:55], v[140:141], v[226:227]
	v_pk_fma_f32 v[52:53], v[52:53], v[138:139], v[224:225]
	v_mul_f32_e32 v139, v55, v55
	v_mul_f32_e32 v138, v53, v53
	v_fmac_f32_e32 v138, v52, v52
	v_fmac_f32_e32 v139, v54, v54
	v_pk_fma_f32 v[40:41], v[40:41], v[142:143], v[220:221]
	v_add_f32_e32 v138, v138, v139
	v_mul_f32_e32 v139, v41, v41
	v_mul_f32_e32 v140, v43, v43
	v_fmac_f32_e32 v139, v40, v40
	v_fmac_f32_e32 v140, v42, v42
	v_add_f32_e32 v139, v139, v140
	v_add_f32_e32 v165, v138, v139
	s_waitcnt vmcnt(0)
	v_pk_fma_f32 v[14:15], v[14:15], v[132:133], v[230:231]
	s_waitcnt vmcnt(0)
	v_pk_fma_f32 v[22:23], v[22:23], v[136:137], v[234:235]
	v_pk_fma_f32 v[20:21], v[20:21], v[134:135], v[232:233]
	v_mul_f32_e32 v135, v23, v23
	v_mul_f32_e32 v134, v21, v21
	v_pk_fma_f32 v[12:13], v[12:13], v[130:131], v[228:229]
	v_fmac_f32_e32 v134, v20, v20
	v_fmac_f32_e32 v135, v22, v22
	v_mul_f32_e32 v130, v13, v13
	v_mul_f32_e32 v131, v15, v15
	v_add_f32_e32 v134, v134, v135
	v_fmac_f32_e32 v130, v12, v12
	v_fmac_f32_e32 v131, v14, v14
	v_add_f32_e32 v134, v165, v134
	v_add_f32_e32 v130, v130, v131
	v_add_f32_e32 v130, v134, v130
	ds_bpermute_b32 v131, v183, v130
	s_waitcnt lgkmcnt(0)
	v_add_f32_e32 v130, v130, v131
	ds_bpermute_b32 v131, v184, v130
	s_and_saveexec_b64 s[2:3], vcc
	s_cbranch_execz .LBB0_714
	s_lshl_b32 s10, s10, 2
	s_add_i32 s10, s10, 0
	s_waitcnt lgkmcnt(0)
	v_add_f32_e32 v130, v130, v131
	v_lshl_add_u32 v131, v196, 4, s10
	ds_write_b32 v131, v130 offset:2816
